# attention A tile DMA uses SGPR base + 32-bit lane offset directly (no per-tile 64-bit VALU address adds)
# speedup vs baseline: 1.0038x; 1.0038x over previous
.LBB0_353:
	s_waitcnt lgkmcnt(0)
	s_barrier
	s_add_i32 s38, s63, 3
	s_cmp_ge_i32 s38, s53
	s_cbranch_scc1 .LBB0_355
	s_and_b32 s38, s38, 3
	s_mulk_i32 s38, 0x6000
	s_add_i32 s38, s38, 0
	s_add_i32 m0, s38, s59
	s_add_i32 s38, s38, s60
	global_load_lds_dwordx4 v148, s[24:25]
	s_add_i32 m0, s38, 0x2000
	s_nop 0
	global_load_lds_dwordx4 v130, s[24:25]
	s_add_i32 m0, s38, 0x2400
	s_nop 0
	global_load_lds_dwordx4 v146, s[24:25]

.LBB0_371:
	s_waitcnt lgkmcnt(0)
	s_barrier
	s_add_i32 s28, s34, 3
	s_cmp_ge_i32 s28, s53
	s_cbranch_scc1 .LBB0_373
	s_and_b32 s28, s28, 3
	s_mulk_i32 s28, 0x6000
	s_add_i32 s28, s28, 0
	s_add_i32 m0, s28, s4
	s_add_i32 s28, s28, s36
	global_load_lds_dwordx4 v148, s[26:27]
	s_add_i32 m0, s28, 0x2000
	s_nop 0
	global_load_lds_dwordx4 v128, s[26:27]
	s_add_i32 m0, s28, 0x2400
	s_nop 0
	global_load_lds_dwordx4 v130, s[26:27]
